# diff-attn fast loop: mid-PV barrier makes next tile's K visible, its first 8 K fragment reads issued in the PV tail (2 barriers per tile)
# baseline (speedup 1.0000x reference)
.Lfast_entry:
	s_waitcnt vmcnt(0)
	s_barrier
	ds_read_b128 v[178:181], v226
	ds_read_b128 v[182:185], v226 offset:4096
	ds_read_b128 v[186:189], v227
	ds_read_b128 v[190:193], v227 offset:4096
	ds_read_b128 v[194:197], v228
	ds_read_b128 v[198:201], v228 offset:4096
	ds_read_b128 v[202:205], v230
	ds_read_b128 v[206:209], v230 offset:4096
	s_waitcnt lgkmcnt(0)
.Lfast_loop:
	s_waitcnt vmcnt(0)
	s_barrier
	s_add_u32 s80, s74, s42
	s_addc_u32 s81, s75, s43
	s_add_i32 s4, s55, 0x8000
	s_mov_b32 m0, s4
	s_add_u32 s82, s76, s42
	s_addc_u32 s83, s77, s43
	global_load_lds_dwordx4 v254, s[80:81]
	s_add_i32 m0, s4, 0x1f80
	s_add_u32 s84, s82, 0x54000
	s_addc_u32 s85, s83, 0
	global_load_lds_dwordx4 v254, s[80:81] offset:128
	s_add_i32 m0, s4, 0x4000
	s_nop 0
	global_load_lds_dwordx4 v255, s[82:83]
	s_add_i32 m0, s4, 0x6000
	s_nop 0
	global_load_lds_dwordx4 v255, s[84:85]
	ds_read_b128 v[6:9], v236
	ds_read_b128 v[10:13], v236 offset:32
	ds_read_b128 v[14:17], v236 offset:64
	ds_read_b128 v[238:241], v236 offset:96
	s_waitcnt lgkmcnt(3)
	v_mfma_f32_32x32x16_bf16 v[162:177], v[178:181], v[6:9], 0
	v_mfma_f32_32x32x16_bf16 v[146:161], v[182:185], v[6:9], 0
	ds_read_b128 v[246:249], v236 offset:128
	ds_read_b128 v[250:253], v226 offset:8192
	ds_read_b128 v[6:9], v226 offset:12288
	s_waitcnt lgkmcnt(5)
	v_mfma_f32_32x32x16_bf16 v[162:177], v[186:189], v[10:13], v[162:177]
	v_mfma_f32_32x32x16_bf16 v[146:161], v[190:193], v[10:13], v[146:161]
	ds_read_b128 v[10:13], v236 offset:160
	s_waitcnt lgkmcnt(5)
	v_mfma_f32_32x32x16_bf16 v[162:177], v[194:197], v[14:17], v[162:177]
	v_mfma_f32_32x32x16_bf16 v[146:161], v[198:201], v[14:17], v[146:161]
	ds_read_b128 v[14:17], v227 offset:8192
	s_waitcnt lgkmcnt(5)
	v_mfma_f32_32x32x16_bf16 v[162:177], v[202:205], v[238:241], v[162:177]
	v_mfma_f32_32x32x16_bf16 v[146:161], v[206:209], v[238:241], v[146:161]
	ds_read_b128 v[238:241], v227 offset:12288
	s_waitcnt lgkmcnt(4)
	v_mfma_f32_32x32x16_bf16 v[194:209], v[250:253], v[246:249], 0
	s_waitcnt lgkmcnt(3)
	v_mfma_f32_32x32x16_bf16 v[178:193], v[6:9], v[246:249], 0
	ds_read_b128 v[246:249], v236 offset:192
	ds_read_b128 v[250:253], v228 offset:8192
	ds_read_b128 v[6:9], v228 offset:12288
	s_waitcnt lgkmcnt(4)
	v_mfma_f32_32x32x16_bf16 v[194:209], v[14:17], v[10:13], v[194:209]
	s_waitcnt lgkmcnt(3)
	v_mfma_f32_32x32x16_bf16 v[178:193], v[238:241], v[10:13], v[178:193]
	ds_read_b128 v[10:13], v236 offset:224
	ds_read_b128 v[14:17], v230 offset:8192
	ds_read_b128 v[238:241], v230 offset:12288
	s_waitcnt lgkmcnt(4)
	v_mfma_f32_32x32x16_bf16 v[194:209], v[250:253], v[246:249], v[194:209]
	s_waitcnt lgkmcnt(3)
	v_mfma_f32_32x32x16_bf16 v[178:193], v[6:9], v[246:249], v[178:193]
	s_waitcnt lgkmcnt(1)
	v_mfma_f32_32x32x16_bf16 v[194:209], v[14:17], v[10:13], v[194:209]
	s_waitcnt lgkmcnt(0)
	v_mfma_f32_32x32x16_bf16 v[178:193], v[238:241], v[10:13], v[178:193]
	v_exp_f32_e32 v166, v166
	v_exp_f32_e32 v167, v167
	v_exp_f32_e32 v168, v168
	v_exp_f32_e32 v169, v169
	s_nop 6
	v_exp_f32_e32 v2, v194
	v_exp_f32_e32 v194, v195
	v_exp_f32_e32 v195, v196
	v_exp_f32_e32 v196, v197
	v_exp_f32_e32 v197, v198
	v_exp_f32_e32 v198, v199
	v_exp_f32_e32 v199, v200
	v_exp_f32_e32 v200, v201
	v_exp_f32_e32 v201, v162
	v_exp_f32_e32 v237, v163
	v_exp_f32_e32 v238, v164
	v_exp_f32_e32 v239, v165
	v_cvt_pk_bf16_f32 v6, v201, v237
	v_cvt_pk_bf16_f32 v7, v238, v239
	v_cvt_pk_bf16_f32 v8, v166, v167
	v_cvt_pk_bf16_f32 v9, v168, v169
	ds_read_b64_tr_b16 v[10:11], v231 offset:16384
	ds_read_b64_tr_b16 v[12:13], v231 offset:18432
	v_cvt_pk_bf16_f32 v14, v2, v194
	ds_read_b64_tr_b16 v[162:163], v232 offset:16384
	ds_read_b64_tr_b16 v[164:165], v232 offset:18432
	v_cvt_pk_bf16_f32 v15, v195, v196
	v_cvt_pk_bf16_f32 v16, v197, v198
	v_cvt_pk_bf16_f32 v17, v199, v200
	s_waitcnt lgkmcnt(2)
	v_mfma_f32_32x32x16_bf16 v[82:97], v[6:9], v[10:13], v[82:97]
	v_exp_f32_e32 v202, v202
	v_exp_f32_e32 v203, v203
	v_exp_f32_e32 v204, v204
	v_exp_f32_e32 v205, v205
	v_exp_f32_e32 v206, v206
	v_exp_f32_e32 v207, v207
	v_exp_f32_e32 v208, v208
	v_mfma_f32_32x32x16_bf16 v[130:145], v[14:17], v[10:13], v[130:145]
	ds_read_b64_tr_b16 v[10:11], v233 offset:16384
	ds_read_b64_tr_b16 v[12:13], v233 offset:18432
	v_exp_f32_e32 v170, v170
	v_exp_f32_e32 v171, v171
	v_exp_f32_e32 v172, v172
	v_exp_f32_e32 v173, v173
	v_exp_f32_e32 v174, v174
	v_exp_f32_e32 v175, v175
	s_waitcnt lgkmcnt(2)
	v_mfma_f32_32x32x16_bf16 v[66:81], v[6:9], v[162:165], v[66:81]
	v_exp_f32_e32 v176, v176
	v_exp_f32_e32 v177, v177
	v_exp_f32_e32 v209, v209
	v_exp_f32_e32 v178, v178
	v_exp_f32_e32 v179, v179
	v_exp_f32_e32 v180, v180
	v_exp_f32_e32 v181, v181
	v_mfma_f32_32x32x16_bf16 v[114:129], v[14:17], v[162:165], v[114:129]
	ds_read_b64_tr_b16 v[162:163], v234 offset:16384
	ds_read_b64_tr_b16 v[164:165], v234 offset:18432
	v_add_f32_e32 v2, v178, v2
	v_add_f32_e32 v2, 0, v2
	v_add_f32_e32 v194, v179, v194
	v_add_f32_e32 v2, v194, v2
	v_add_f32_e32 v194, v180, v195
	s_waitcnt lgkmcnt(2)
	v_mfma_f32_32x32x16_bf16 v[34:49], v[6:9], v[10:13], v[34:49]
	v_add_f32_e32 v2, v194, v2
	v_add_f32_e32 v194, v181, v196
	v_add_f32_e32 v2, v194, v2
	v_exp_f32_e32 v182, v182
	v_exp_f32_e32 v183, v183
	v_exp_f32_e32 v184, v184
	v_exp_f32_e32 v194, v146
	v_mfma_f32_32x32x16_bf16 v[98:113], v[14:17], v[10:13], v[98:113]
	ds_read_b64_tr_b16 v[10:11], v231 offset:20480
	ds_read_b64_tr_b16 v[12:13], v231 offset:22528
	v_exp_f32_e32 v195, v147
	v_exp_f32_e32 v196, v148
	v_exp_f32_e32 v244, v149
	v_exp_f32_e32 v150, v150
	v_exp_f32_e32 v151, v151
	v_exp_f32_e32 v152, v152
	s_waitcnt lgkmcnt(2)
	v_mfma_f32_32x32x16_bf16 v[18:33], v[6:9], v[162:165], v[18:33]
	v_cvt_pk_bf16_f32 v6, v170, v171
	v_cvt_pk_bf16_f32 v7, v172, v173
	v_cvt_pk_bf16_f32 v8, v174, v175
	v_cvt_pk_bf16_f32 v9, v176, v177
	v_exp_f32_e32 v153, v153
	v_exp_f32_e32 v154, v154
	v_exp_f32_e32 v155, v155
	v_mfma_f32_32x32x16_bf16 v[50:65], v[14:17], v[162:165], v[50:65]
	v_cvt_pk_bf16_f32 v14, v202, v203
	ds_read_b64_tr_b16 v[162:163], v232 offset:20480
	ds_read_b64_tr_b16 v[164:165], v232 offset:22528
	v_cvt_pk_bf16_f32 v15, v204, v205
	v_cvt_pk_bf16_f32 v16, v206, v207
	v_cvt_pk_bf16_f32 v17, v208, v209
	v_exp_f32_e32 v156, v156
	s_waitcnt lgkmcnt(2)
	v_mfma_f32_32x32x16_bf16 v[82:97], v[6:9], v[10:13], v[82:97]
	v_exp_f32_e32 v157, v157
	v_exp_f32_e32 v158, v158
	v_exp_f32_e32 v159, v159
	v_exp_f32_e32 v160, v160
	v_exp_f32_e32 v161, v161
	s_add_u32 s42, s42, 0xa8000
	s_addc_u32 s43, s43, 0
	v_mfma_f32_32x32x16_bf16 v[130:145], v[14:17], v[10:13], v[130:145]
	ds_read_b64_tr_b16 v[10:11], v233 offset:20480
	ds_read_b64_tr_b16 v[12:13], v233 offset:22528
	s_waitcnt lgkmcnt(2)
	v_mfma_f32_32x32x16_bf16 v[66:81], v[6:9], v[162:165], v[66:81]
	v_mfma_f32_32x32x16_bf16 v[114:129], v[14:17], v[162:165], v[114:129]
	ds_read_b64_tr_b16 v[162:163], v234 offset:20480
	ds_read_b64_tr_b16 v[164:165], v234 offset:22528
	s_waitcnt lgkmcnt(0)
	v_mfma_f32_32x32x16_bf16 v[18:33], v[6:9], v[162:165], v[18:33]
	v_mfma_f32_32x32x16_bf16 v[50:65], v[14:17], v[162:165], v[50:65]
	v_exp_f32_e32 v162, v185
	v_add_f32_e32 v163, v182, v197
	v_add_f32_e32 v2, v163, v2
	v_add_f32_e32 v163, v183, v198
	v_add_f32_e32 v2, v163, v2
	v_exp_f32_e32 v163, v186
	v_exp_f32_e32 v164, v188
	v_mfma_f32_32x32x16_bf16 v[34:49], v[6:9], v[10:13], v[34:49]
	v_cvt_pk_bf16_f32 v6, v194, v195
	v_cvt_pk_bf16_f32 v7, v196, v244
	v_cvt_pk_bf16_f32 v8, v150, v151
	v_cvt_pk_bf16_f32 v9, v152, v153
	v_exp_f32_e32 v165, v189
	v_mfma_f32_32x32x16_bf16 v[98:113], v[14:17], v[10:13], v[98:113]
	s_waitcnt vmcnt(0)
	s_barrier
	ds_read_b64_tr_b16 v[10:11], v231 offset:24576
	ds_read_b64_tr_b16 v[12:13], v231 offset:26624
	v_cvt_pk_bf16_f32 v14, v178, v179
	v_cvt_pk_bf16_f32 v15, v180, v181
	v_cvt_pk_bf16_f32 v16, v182, v183
	v_cvt_pk_bf16_f32 v17, v184, v162
	ds_read_b64_tr_b16 v[146:147], v232 offset:24576
	ds_read_b64_tr_b16 v[148:149], v232 offset:26624
	v_add_f32_e32 v178, v165, v205
	s_waitcnt lgkmcnt(2)
	v_mfma_f32_32x32x16_bf16 v[82:97], v[6:9], v[10:13], v[82:97]
	v_exp_f32_e32 v179, v190
	s_nop 0
	v_add_f32_e32 v180, v179, v206
	v_mfma_f32_32x32x16_bf16 v[130:145], v[14:17], v[10:13], v[130:145]
	v_add_f32_e32 v10, v184, v199
	ds_read_b128 v[182:185], v226 offset:36864
	v_add_f32_e32 v2, v10, v2
	v_add_f32_e32 v10, v162, v200
	v_exp_f32_e32 v162, v187
	ds_read_b128 v[186:189], v227 offset:32768
	v_add_f32_e32 v2, v10, v2
	v_add_f32_e32 v10, v163, v202
	v_add_f32_e32 v2, v10, v2
	v_add_f32_e32 v10, v162, v203
	v_add_f32_e32 v2, v10, v2
	v_add_f32_e32 v10, v164, v204
	ds_read_b128 v[202:205], v230 offset:32768
	v_add_f32_e32 v2, v10, v2
	v_add_f32_e32 v2, v178, v2
	v_exp_f32_e32 v178, v191
	ds_read_b64_tr_b16 v[10:11], v233 offset:24576
	ds_read_b64_tr_b16 v[12:13], v233 offset:26624
	s_waitcnt lgkmcnt(5)
	v_mfma_f32_32x32x16_bf16 v[66:81], v[6:9], v[146:149], v[66:81]
	v_add_f32_e32 v2, v180, v2
	v_exp_f32_e32 v180, v192
	v_add_f32_e32 v181, v178, v207
	v_add_f32_e32 v2, v181, v2
	v_exp_f32_e32 v181, v193
	ds_read_b128 v[190:193], v227 offset:36864
	v_mfma_f32_32x32x16_bf16 v[114:129], v[14:17], v[146:149], v[114:129]
	ds_read_b64_tr_b16 v[146:147], v234 offset:24576
	ds_read_b64_tr_b16 v[148:149], v234 offset:26624
	s_waitcnt lgkmcnt(3)
	v_mfma_f32_32x32x16_bf16 v[34:49], v[6:9], v[10:13], v[34:49]
	v_mfma_f32_32x32x16_bf16 v[98:113], v[14:17], v[10:13], v[98:113]
	v_add_f32_e32 v10, v180, v208
	v_add_f32_e32 v2, v10, v2
	ds_read_b64_tr_b16 v[10:11], v231 offset:28672
	ds_read_b64_tr_b16 v[12:13], v231 offset:30720
	s_waitcnt lgkmcnt(2)
	v_mfma_f32_32x32x16_bf16 v[18:33], v[6:9], v[146:149], v[18:33]
	v_cvt_pk_bf16_f32 v6, v154, v155
	v_cvt_pk_bf16_f32 v7, v156, v157
	v_cvt_pk_bf16_f32 v8, v158, v159
	v_cvt_pk_bf16_f32 v9, v160, v161
	v_mfma_f32_32x32x16_bf16 v[50:65], v[14:17], v[146:149], v[50:65]
	v_cvt_pk_bf16_f32 v14, v163, v162
	v_cvt_pk_bf16_f32 v15, v164, v165
	v_cvt_pk_bf16_f32 v16, v179, v178
	v_cvt_pk_bf16_f32 v17, v180, v181
	v_add_f32_e32 v162, v181, v209
	ds_read_b128 v[178:181], v226 offset:32768
	ds_read_b128 v[206:209], v230 offset:36864
	v_add_f32_e32 v2, v162, v2
	v_add_f32_e32 v4, v4, v2
	v_add_f32_e32 v2, v194, v201
	ds_read_b128 v[198:201], v228 offset:36864
	s_waitcnt lgkmcnt(3)
	v_mfma_f32_32x32x16_bf16 v[82:97], v[6:9], v[10:13], v[82:97]
	v_add_f32_e32 v2, 0, v2
	ds_read_b64_tr_b16 v[146:147], v232 offset:28672
	ds_read_b64_tr_b16 v[148:149], v232 offset:30720
	v_mfma_f32_32x32x16_bf16 v[130:145], v[14:17], v[10:13], v[130:145]
	v_add_f32_e32 v10, v195, v237
	v_add_f32_e32 v2, v10, v2
	v_add_f32_e32 v10, v196, v238
	ds_read_b128 v[194:197], v228 offset:32768
	v_add_f32_e32 v2, v10, v2
	v_add_f32_e32 v10, v244, v239
	v_add_f32_e32 v2, v10, v2
	v_add_f32_e32 v10, v150, v166
	v_add_f32_e32 v2, v10, v2
	v_add_f32_e32 v10, v151, v167
	v_add_f32_e32 v2, v10, v2
	v_add_f32_e32 v10, v152, v168
	s_waitcnt lgkmcnt(1)
	v_mfma_f32_32x32x16_bf16 v[66:81], v[6:9], v[146:149], v[66:81]
	v_add_f32_e32 v2, v10, v2
	ds_read_b64_tr_b16 v[10:11], v233 offset:28672
	ds_read_b64_tr_b16 v[12:13], v233 offset:30720
	v_add_f32_e32 v150, v153, v169
	v_add_f32_e32 v2, v150, v2
	v_add_f32_e32 v150, v154, v170
	v_add_f32_e32 v2, v150, v2
	v_add_f32_e32 v150, v155, v171
	v_mfma_f32_32x32x16_bf16 v[114:129], v[14:17], v[146:149], v[114:129]
	ds_read_b64_tr_b16 v[146:147], v234 offset:28672
	ds_read_b64_tr_b16 v[148:149], v234 offset:30720
	v_add_f32_e32 v2, v150, v2
	v_add_f32_e32 v150, v156, v172
	v_add_f32_e32 v2, v150, v2
	v_add_f32_e32 v150, v157, v173
	v_add_f32_e32 v2, v150, v2
	s_waitcnt lgkmcnt(2)
	v_mfma_f32_32x32x16_bf16 v[34:49], v[6:9], v[10:13], v[34:49]
	v_mfma_f32_32x32x16_bf16 v[98:113], v[14:17], v[10:13], v[98:113]
	v_add_f32_e32 v10, v158, v174
	v_add_f32_e32 v2, v10, v2
	v_add_f32_e32 v10, v159, v175
	v_add_f32_e32 v2, v10, v2
	v_add_f32_e32 v10, v160, v176
	v_add_f32_e32 v2, v10, v2
	v_add_f32_e32 v10, v161, v177
	s_waitcnt lgkmcnt(0)
	v_mfma_f32_32x32x16_bf16 v[18:33], v[6:9], v[146:149], v[18:33]
	v_add_f32_e32 v2, v10, v2
	v_add_f32_e32 v235, v235, v2
	v_mfma_f32_32x32x16_bf16 v[50:65], v[14:17], v[146:149], v[50:65]
	s_waitcnt vmcnt(0)
	s_barrier
	s_cmp_eq_u32 s42, 0x5358000
	s_cbranch_scc1 .Lfast_skip_dma
	s_add_u32 s80, s74, s42
	s_addc_u32 s81, s75, s43
	s_add_i32 s4, s55, 0
	s_mov_b32 m0, s4
	s_add_u32 s82, s76, s42
	s_addc_u32 s83, s77, s43
	global_load_lds_dwordx4 v254, s[80:81]
	s_add_i32 m0, s4, 0x1f80
	s_add_u32 s84, s82, 0x54000
	s_addc_u32 s85, s83, 0
	global_load_lds_dwordx4 v254, s[80:81] offset:128
	s_add_i32 m0, s4, 0x4000
	s_nop 0
	global_load_lds_dwordx4 v255, s[82:83]
	s_add_i32 m0, s4, 0x6000
	s_nop 0
	global_load_lds_dwordx4 v255, s[84:85]
.Lfast_skip_dma:
	ds_read_b128 v[6:9], v236
	ds_read_b128 v[10:13], v236 offset:32
	ds_read_b128 v[14:17], v236 offset:64
	ds_read_b128 v[238:241], v236 offset:96
	s_waitcnt lgkmcnt(3)
	v_mfma_f32_32x32x16_bf16 v[162:177], v[178:181], v[6:9], 0
	v_mfma_f32_32x32x16_bf16 v[146:161], v[182:185], v[6:9], 0
	ds_read_b128 v[246:249], v236 offset:128
	ds_read_b128 v[250:253], v226 offset:40960
	ds_read_b128 v[6:9], v226 offset:45056
	s_waitcnt lgkmcnt(5)
	v_mfma_f32_32x32x16_bf16 v[162:177], v[186:189], v[10:13], v[162:177]
	v_mfma_f32_32x32x16_bf16 v[146:161], v[190:193], v[10:13], v[146:161]
	ds_read_b128 v[10:13], v236 offset:160
	s_waitcnt lgkmcnt(5)
	v_mfma_f32_32x32x16_bf16 v[162:177], v[194:197], v[14:17], v[162:177]
	v_mfma_f32_32x32x16_bf16 v[146:161], v[198:201], v[14:17], v[146:161]
	ds_read_b128 v[14:17], v227 offset:40960
	s_waitcnt lgkmcnt(5)
	v_mfma_f32_32x32x16_bf16 v[162:177], v[202:205], v[238:241], v[162:177]
	v_mfma_f32_32x32x16_bf16 v[146:161], v[206:209], v[238:241], v[146:161]
	ds_read_b128 v[238:241], v227 offset:45056
	s_waitcnt lgkmcnt(4)
	v_mfma_f32_32x32x16_bf16 v[194:209], v[250:253], v[246:249], 0
	s_waitcnt lgkmcnt(3)
	v_mfma_f32_32x32x16_bf16 v[178:193], v[6:9], v[246:249], 0
	ds_read_b128 v[246:249], v236 offset:192
	ds_read_b128 v[250:253], v228 offset:40960
	ds_read_b128 v[6:9], v228 offset:45056
	s_waitcnt lgkmcnt(4)
	v_mfma_f32_32x32x16_bf16 v[194:209], v[14:17], v[10:13], v[194:209]
	s_waitcnt lgkmcnt(3)
	v_mfma_f32_32x32x16_bf16 v[178:193], v[238:241], v[10:13], v[178:193]
	ds_read_b128 v[10:13], v236 offset:224
	ds_read_b128 v[14:17], v230 offset:40960
	ds_read_b128 v[238:241], v230 offset:45056
	s_waitcnt lgkmcnt(4)
	v_mfma_f32_32x32x16_bf16 v[194:209], v[250:253], v[246:249], v[194:209]
	s_waitcnt lgkmcnt(3)
	v_mfma_f32_32x32x16_bf16 v[178:193], v[6:9], v[246:249], v[178:193]
	s_waitcnt lgkmcnt(1)
	v_mfma_f32_32x32x16_bf16 v[194:209], v[14:17], v[10:13], v[194:209]
	s_waitcnt lgkmcnt(0)
	v_mfma_f32_32x32x16_bf16 v[178:193], v[238:241], v[10:13], v[178:193]
	v_exp_f32_e32 v166, v166
	v_exp_f32_e32 v167, v167
	v_exp_f32_e32 v168, v168
	v_exp_f32_e32 v169, v169
	s_nop 6
	v_exp_f32_e32 v2, v194
	v_exp_f32_e32 v194, v195
	v_exp_f32_e32 v195, v196
	v_exp_f32_e32 v196, v197
	v_exp_f32_e32 v197, v198
	v_exp_f32_e32 v198, v199
	v_exp_f32_e32 v199, v200
	v_exp_f32_e32 v200, v201
	v_exp_f32_e32 v201, v162
	v_exp_f32_e32 v237, v163
	v_exp_f32_e32 v238, v164
	v_exp_f32_e32 v239, v165
	v_cvt_pk_bf16_f32 v6, v201, v237
	v_cvt_pk_bf16_f32 v7, v238, v239
	v_cvt_pk_bf16_f32 v8, v166, v167
	v_cvt_pk_bf16_f32 v9, v168, v169
	ds_read_b64_tr_b16 v[10:11], v231 offset:49152
	ds_read_b64_tr_b16 v[12:13], v231 offset:51200
	v_cvt_pk_bf16_f32 v14, v2, v194
	ds_read_b64_tr_b16 v[162:163], v232 offset:49152
	ds_read_b64_tr_b16 v[164:165], v232 offset:51200
	v_cvt_pk_bf16_f32 v15, v195, v196
	v_cvt_pk_bf16_f32 v16, v197, v198
	v_cvt_pk_bf16_f32 v17, v199, v200
	s_waitcnt lgkmcnt(2)
	v_mfma_f32_32x32x16_bf16 v[82:97], v[6:9], v[10:13], v[82:97]
	v_exp_f32_e32 v202, v202
	v_exp_f32_e32 v203, v203
	v_exp_f32_e32 v204, v204
	v_exp_f32_e32 v205, v205
	v_exp_f32_e32 v206, v206
	v_exp_f32_e32 v207, v207
	v_exp_f32_e32 v208, v208
	v_mfma_f32_32x32x16_bf16 v[130:145], v[14:17], v[10:13], v[130:145]
	ds_read_b64_tr_b16 v[10:11], v233 offset:49152
	ds_read_b64_tr_b16 v[12:13], v233 offset:51200
	v_exp_f32_e32 v170, v170
	v_exp_f32_e32 v171, v171
	v_exp_f32_e32 v172, v172
	v_exp_f32_e32 v173, v173
	v_exp_f32_e32 v174, v174
	v_exp_f32_e32 v175, v175
	s_waitcnt lgkmcnt(2)
	v_mfma_f32_32x32x16_bf16 v[66:81], v[6:9], v[162:165], v[66:81]
	v_exp_f32_e32 v176, v176
	v_exp_f32_e32 v177, v177
	v_exp_f32_e32 v209, v209
	v_exp_f32_e32 v178, v178
	v_exp_f32_e32 v179, v179
	v_exp_f32_e32 v180, v180
	v_exp_f32_e32 v181, v181
	v_mfma_f32_32x32x16_bf16 v[114:129], v[14:17], v[162:165], v[114:129]
	ds_read_b64_tr_b16 v[162:163], v234 offset:49152
	ds_read_b64_tr_b16 v[164:165], v234 offset:51200
	v_add_f32_e32 v2, v178, v2
	v_add_f32_e32 v2, 0, v2
	v_add_f32_e32 v194, v179, v194
	v_add_f32_e32 v2, v194, v2
	v_add_f32_e32 v194, v180, v195
	s_waitcnt lgkmcnt(2)
	v_mfma_f32_32x32x16_bf16 v[34:49], v[6:9], v[10:13], v[34:49]
	v_add_f32_e32 v2, v194, v2
	v_add_f32_e32 v194, v181, v196
	v_add_f32_e32 v2, v194, v2
	v_exp_f32_e32 v182, v182
	v_exp_f32_e32 v183, v183
	v_exp_f32_e32 v184, v184
	v_exp_f32_e32 v194, v146
	v_mfma_f32_32x32x16_bf16 v[98:113], v[14:17], v[10:13], v[98:113]
	ds_read_b64_tr_b16 v[10:11], v231 offset:53248
	ds_read_b64_tr_b16 v[12:13], v231 offset:55296
	v_exp_f32_e32 v195, v147
	v_exp_f32_e32 v196, v148
	v_exp_f32_e32 v244, v149
	v_exp_f32_e32 v150, v150
	v_exp_f32_e32 v151, v151
	v_exp_f32_e32 v152, v152
	s_waitcnt lgkmcnt(2)
	v_mfma_f32_32x32x16_bf16 v[18:33], v[6:9], v[162:165], v[18:33]
	v_cvt_pk_bf16_f32 v6, v170, v171
	v_cvt_pk_bf16_f32 v7, v172, v173
	v_cvt_pk_bf16_f32 v8, v174, v175
	v_cvt_pk_bf16_f32 v9, v176, v177
	v_exp_f32_e32 v153, v153
	v_exp_f32_e32 v154, v154
	v_exp_f32_e32 v155, v155
	v_mfma_f32_32x32x16_bf16 v[50:65], v[14:17], v[162:165], v[50:65]
	v_cvt_pk_bf16_f32 v14, v202, v203
	ds_read_b64_tr_b16 v[162:163], v232 offset:53248
	ds_read_b64_tr_b16 v[164:165], v232 offset:55296
	v_cvt_pk_bf16_f32 v15, v204, v205
	v_cvt_pk_bf16_f32 v16, v206, v207
	v_cvt_pk_bf16_f32 v17, v208, v209
	v_exp_f32_e32 v156, v156
	s_waitcnt lgkmcnt(2)
	v_mfma_f32_32x32x16_bf16 v[82:97], v[6:9], v[10:13], v[82:97]
	v_exp_f32_e32 v157, v157
	v_exp_f32_e32 v158, v158
	v_exp_f32_e32 v159, v159
	v_exp_f32_e32 v160, v160
	v_exp_f32_e32 v161, v161
	s_add_u32 s42, s42, 0xa8000
	s_addc_u32 s43, s43, 0
	v_mfma_f32_32x32x16_bf16 v[130:145], v[14:17], v[10:13], v[130:145]
	ds_read_b64_tr_b16 v[10:11], v233 offset:53248
	ds_read_b64_tr_b16 v[12:13], v233 offset:55296
	s_cmp_eq_u32 s42, 0x5400000
	s_waitcnt lgkmcnt(2)
	v_mfma_f32_32x32x16_bf16 v[66:81], v[6:9], v[162:165], v[66:81]
	v_mfma_f32_32x32x16_bf16 v[114:129], v[14:17], v[162:165], v[114:129]
	ds_read_b64_tr_b16 v[162:163], v234 offset:53248
	ds_read_b64_tr_b16 v[164:165], v234 offset:55296
	s_waitcnt lgkmcnt(0)
	v_mfma_f32_32x32x16_bf16 v[18:33], v[6:9], v[162:165], v[18:33]
	v_mfma_f32_32x32x16_bf16 v[50:65], v[14:17], v[162:165], v[50:65]
	v_exp_f32_e32 v162, v185
	v_add_f32_e32 v163, v182, v197
	v_add_f32_e32 v2, v163, v2
	v_add_f32_e32 v163, v183, v198
	v_add_f32_e32 v2, v163, v2
	v_exp_f32_e32 v163, v186
	v_exp_f32_e32 v164, v188
	v_mfma_f32_32x32x16_bf16 v[34:49], v[6:9], v[10:13], v[34:49]
	v_cvt_pk_bf16_f32 v6, v194, v195
	v_cvt_pk_bf16_f32 v7, v196, v244
	v_cvt_pk_bf16_f32 v8, v150, v151
	v_cvt_pk_bf16_f32 v9, v152, v153
	v_exp_f32_e32 v165, v189
	v_mfma_f32_32x32x16_bf16 v[98:113], v[14:17], v[10:13], v[98:113]
	s_waitcnt vmcnt(0)
	s_barrier
	ds_read_b64_tr_b16 v[10:11], v231 offset:57344
	ds_read_b64_tr_b16 v[12:13], v231 offset:59392
	v_cvt_pk_bf16_f32 v14, v178, v179
	v_cvt_pk_bf16_f32 v15, v180, v181
	v_cvt_pk_bf16_f32 v16, v182, v183
	v_cvt_pk_bf16_f32 v17, v184, v162
	ds_read_b64_tr_b16 v[146:147], v232 offset:57344
	ds_read_b64_tr_b16 v[148:149], v232 offset:59392
	v_add_f32_e32 v178, v165, v205
	s_waitcnt lgkmcnt(2)
	v_mfma_f32_32x32x16_bf16 v[82:97], v[6:9], v[10:13], v[82:97]
	v_exp_f32_e32 v179, v190
	s_nop 0
	v_add_f32_e32 v180, v179, v206
	v_mfma_f32_32x32x16_bf16 v[130:145], v[14:17], v[10:13], v[130:145]
	v_add_f32_e32 v10, v184, v199
	ds_read_b128 v[182:185], v226 offset:4096
	v_add_f32_e32 v2, v10, v2
	v_add_f32_e32 v10, v162, v200
	v_exp_f32_e32 v162, v187
	ds_read_b128 v[186:189], v227
	v_add_f32_e32 v2, v10, v2
	v_add_f32_e32 v10, v163, v202
	v_add_f32_e32 v2, v10, v2
	v_add_f32_e32 v10, v162, v203
	v_add_f32_e32 v2, v10, v2
	v_add_f32_e32 v10, v164, v204
	ds_read_b128 v[202:205], v230
	v_add_f32_e32 v2, v10, v2
	v_add_f32_e32 v2, v178, v2
	v_exp_f32_e32 v178, v191
	ds_read_b64_tr_b16 v[10:11], v233 offset:57344
	ds_read_b64_tr_b16 v[12:13], v233 offset:59392
	s_waitcnt lgkmcnt(5)
	v_mfma_f32_32x32x16_bf16 v[66:81], v[6:9], v[146:149], v[66:81]
	v_add_f32_e32 v2, v180, v2
	v_exp_f32_e32 v180, v192
	v_add_f32_e32 v181, v178, v207
	v_add_f32_e32 v2, v181, v2
	v_exp_f32_e32 v181, v193
	ds_read_b128 v[190:193], v227 offset:4096
	v_mfma_f32_32x32x16_bf16 v[114:129], v[14:17], v[146:149], v[114:129]
	ds_read_b64_tr_b16 v[146:147], v234 offset:57344
	ds_read_b64_tr_b16 v[148:149], v234 offset:59392
	s_waitcnt lgkmcnt(3)
	v_mfma_f32_32x32x16_bf16 v[34:49], v[6:9], v[10:13], v[34:49]
	v_mfma_f32_32x32x16_bf16 v[98:113], v[14:17], v[10:13], v[98:113]
	v_add_f32_e32 v10, v180, v208
	v_add_f32_e32 v2, v10, v2
	ds_read_b64_tr_b16 v[10:11], v231 offset:61440
	ds_read_b64_tr_b16 v[12:13], v231 offset:63488
	s_waitcnt lgkmcnt(2)
	v_mfma_f32_32x32x16_bf16 v[18:33], v[6:9], v[146:149], v[18:33]
	v_cvt_pk_bf16_f32 v6, v154, v155
	v_cvt_pk_bf16_f32 v7, v156, v157
	v_cvt_pk_bf16_f32 v8, v158, v159
	v_cvt_pk_bf16_f32 v9, v160, v161
	v_mfma_f32_32x32x16_bf16 v[50:65], v[14:17], v[146:149], v[50:65]
	v_cvt_pk_bf16_f32 v14, v163, v162
	v_cvt_pk_bf16_f32 v15, v164, v165
	v_cvt_pk_bf16_f32 v16, v179, v178
	v_cvt_pk_bf16_f32 v17, v180, v181
	v_add_f32_e32 v162, v181, v209
	ds_read_b128 v[178:181], v226
	ds_read_b128 v[206:209], v230 offset:4096
	v_add_f32_e32 v2, v162, v2
	v_add_f32_e32 v4, v4, v2
	v_add_f32_e32 v2, v194, v201
	ds_read_b128 v[198:201], v228 offset:4096
	s_waitcnt lgkmcnt(3)
	v_mfma_f32_32x32x16_bf16 v[82:97], v[6:9], v[10:13], v[82:97]
	v_add_f32_e32 v2, 0, v2
	ds_read_b64_tr_b16 v[146:147], v232 offset:61440
	ds_read_b64_tr_b16 v[148:149], v232 offset:63488
	v_mfma_f32_32x32x16_bf16 v[130:145], v[14:17], v[10:13], v[130:145]
	v_add_f32_e32 v10, v195, v237
	v_add_f32_e32 v2, v10, v2
	v_add_f32_e32 v10, v196, v238
	ds_read_b128 v[194:197], v228
	v_add_f32_e32 v2, v10, v2
	v_add_f32_e32 v10, v244, v239
	v_add_f32_e32 v2, v10, v2
	v_add_f32_e32 v10, v150, v166
	v_add_f32_e32 v2, v10, v2
	v_add_f32_e32 v10, v151, v167
	v_add_f32_e32 v2, v10, v2
	v_add_f32_e32 v10, v152, v168
	s_waitcnt lgkmcnt(1)
	v_mfma_f32_32x32x16_bf16 v[66:81], v[6:9], v[146:149], v[66:81]
	v_add_f32_e32 v2, v10, v2
	ds_read_b64_tr_b16 v[10:11], v233 offset:61440
	ds_read_b64_tr_b16 v[12:13], v233 offset:63488
	v_add_f32_e32 v150, v153, v169
	v_add_f32_e32 v2, v150, v2
	v_add_f32_e32 v150, v154, v170
	v_add_f32_e32 v2, v150, v2
	v_add_f32_e32 v150, v155, v171
	v_mfma_f32_32x32x16_bf16 v[114:129], v[14:17], v[146:149], v[114:129]
	ds_read_b64_tr_b16 v[146:147], v234 offset:61440
	ds_read_b64_tr_b16 v[148:149], v234 offset:63488
	v_add_f32_e32 v2, v150, v2
	v_add_f32_e32 v150, v156, v172
	v_add_f32_e32 v2, v150, v2
	v_add_f32_e32 v150, v157, v173
	v_add_f32_e32 v2, v150, v2
	s_waitcnt lgkmcnt(2)
	v_mfma_f32_32x32x16_bf16 v[34:49], v[6:9], v[10:13], v[34:49]
	v_mfma_f32_32x32x16_bf16 v[98:113], v[14:17], v[10:13], v[98:113]
	v_add_f32_e32 v10, v158, v174
	v_add_f32_e32 v2, v10, v2
	v_add_f32_e32 v10, v159, v175
	v_add_f32_e32 v2, v10, v2
	v_add_f32_e32 v10, v160, v176
	v_add_f32_e32 v2, v10, v2
	v_add_f32_e32 v10, v161, v177
	s_waitcnt lgkmcnt(0)
	v_mfma_f32_32x32x16_bf16 v[18:33], v[6:9], v[146:149], v[18:33]
	v_add_f32_e32 v2, v10, v2
	v_add_f32_e32 v235, v235, v2
	v_mfma_f32_32x32x16_bf16 v[50:65], v[14:17], v[146:149], v[50:65]
	s_cbranch_scc0 .Lfast_loop
.LBB0_453:
	s_waitcnt lgkmcnt(0)
	s_setprio 0
	v_mov_b32_e32 v2, v235
	v_mov_b32_e32 v5, v4
	s_nop 0
	v_permlane32_swap_b32_e32 v235, v2
	v_permlane32_swap_b32_e32 v4, v5
	s_cmp_lg_u32 s68, 0
	s_cbranch_scc1 .Lsafe_done
	v_add_f32_e32 v6, v235, v2
	v_add_f32_e32 v7, v4, v5
	s_mov_b32 s69, 0x1f800000
	s_mov_b32 s70, 0x71800000
	v_cmp_nge_f32_e64 s[4:5], v6, s69
	v_cmp_nle_f32_e64 s[6:7], v6, s70
	s_or_b64 s[4:5], s[4:5], s[6:7]
	v_cmp_nge_f32_e64 s[6:7], v7, s69
	s_or_b64 s[4:5], s[4:5], s[6:7]
	v_cmp_nle_f32_e64 s[6:7], v7, s70
	s_or_b64 s[4:5], s[4:5], s[6:7]
	s_cmp_eq_u64 s[4:5], 0
	s_cbranch_scc1 .Lflag_skip
	v_mov_b32_e32 v6, 0x21800
	v_mov_b32_e32 v7, 1
	ds_write_b32 v6, v7
